# prompt attention: counted vmcnt waits (2-tile K/V prefetch stays in flight) + static prio for waves 4-7
# speedup vs baseline: 1.0014x; 1.0014x over previous
; #define LAS __attribute__((address_space(3)))
; #define BID() opq_s((int)blockIdx.x)
; #define GDIM() opq_s((int)gridDim.x)
; DEVI unsigned char* WSP() { return *(unsigned char* const __attribute__((address_space(4)))*)(kargs() + 8 * 22); }
; DEVI void attn_phase(int wv, LAS unsigned char* lds, int l) {
;     const int G = GDIM(), bx = BID();
;     const int vcu = (G % 8 == 0) ? (bx % 8) * (G / 8) + bx / 8 : bx;
;     for (int pi = vcu; pi < 512; pi += G) {
;         const int bh = pi >> 3, s = pi & 7, b = bh >> 3, h = bh & 7;
; #pragma unroll 1
;         for (int k = 0; k < 2; ++k) {
;             unsigned char* ws = WSP();
;             const float* ssq_qh = (const float*)(ws + O_SSQZ) + (size_t)(7 + 8 * l) * MT;
;             const int qb = k == 0 ? s : 15 - s, q0 = qb * 256; const size_t tok0 = (size_t)b * 4096 + q0;
;             attn_unit_p(wv, lds, (const bf16_t*)(ws + O_QP) + ((size_t)bh * 4096 + q0) * 96, ssq_qh + tok0 * 8 + h, (const bf16_t*)(ws + O_KP) + (size_t)bh * 4096 * 96,
;                              (const bf16_t*)(ws + O_VTP) + (size_t)bh * 64 * 4096, 4096, 4 * qb + 4, 4 * qb, (bf16_t*)(ws + O_ATT) + tok0 * 512 + h * 64);
.LBB0_1282:
	s_or_b64 exec, exec, s[2:3]
	s_mov_b32 s15, s85
	s_waitcnt lgkmcnt(0)
	s_barrier
	s_cmp_lt_u32 s33, 4
	s_cbranch_scc1 .Lprio_p3_skip
	s_setprio 1
.Lprio_p3_skip:
	s_and_b32 s2, s15, 7
	s_mov_b32 s4, s95
	s_cmp_lg_u32 s2, 0
	s_cbranch_scc0 .LBB0_1284
	s_cmpk_gt_i32 s4, 0x1ff
	s_mul_i32 s12, s46, 0x41000
	s_cbranch_scc0 .LBB0_1285
	s_branch .LBB0_1326

; #define AT_LD(K0, K1, V, t) do { K0 = *(const u32x4*)(Kb + (size_t)(t) * 6144 + kp0 * 8); if (two) K1 = *(const u32x4*)(Kb + (size_t)(t) * 6144 + kp1 * 8); V = *(const u32x4*)(vsrc + (size_t)(t) * 64); } while (0)
; #define AT_ST(K0, K1, V, buf) do { LAS unsigned char* b_ = lds + (buf) * AT_TB; *(LAS u32x4*)(b_ + koff0) = K0; if (two) *(LAS u32x4*)(b_ + koff1) = K1; *(LAS u32x4*)(b_ + voffl) = V; } while (0)
; DEVI void attn_unit_p(int wv, LAS unsigned char* lds, const bf16_t* Qb, const float* ssq_q, const bf16_t* Kb, const bf16_t* VTb, int ldv, int NT, int vis0, bf16_t* Ob) {
;     ...
;     for (int t = 0; t < NT; t += 2) {
;         if (t + 2 < NT) AT_LD(kb0, kb1, vbb, t + 2);
;         if (t <= lastvis) at_compute(lds, r32, hi, qr, t == 0, negm, m_run, l_run, o0, o1);
;         AT_ST(ka0, ka1, va, 1);
;         __syncthreads();
;         if (t + 3 < NT) AT_LD(ka0, ka1, va, t + 3);
.LBB0_1300:
	s_cmp_lg_u64 s[62:63], 0
	s_cbranch_scc0 .Lpa_wE0_1
	s_cmp_lg_u64 s[2:3], 0
	s_cbranch_scc0 .Lpa_wE2_1
	s_waitcnt vmcnt(3)
	s_branch .Lpa_wEd_1
.Lpa_wE2_1:
	s_waitcnt vmcnt(2)
	s_branch .Lpa_wEd_1

; #define AT_LD(K0, K1, V, t) do { K0 = *(const u32x4*)(Kb + (size_t)(t) * 6144 + kp0 * 8); if (two) K1 = *(const u32x4*)(Kb + (size_t)(t) * 6144 + kp1 * 8); V = *(const u32x4*)(vsrc + (size_t)(t) * 64); } while (0)
; #define AT_ST(K0, K1, V, buf) do { LAS unsigned char* b_ = lds + (buf) * AT_TB; *(LAS u32x4*)(b_ + koff0) = K0; if (two) *(LAS u32x4*)(b_ + koff1) = K1; *(LAS u32x4*)(b_ + voffl) = V; } while (0)
; DEVI void attn_unit_p(int wv, LAS unsigned char* lds, const bf16_t* Qb, const float* ssq_q, const bf16_t* Kb, const bf16_t* VTb, int ldv, int NT, int vis0, bf16_t* Ob) {
;     ...
;     for (int t = 0; t < NT; t += 2) {
;         if (t + 2 < NT) AT_LD(kb0, kb1, vbb, t + 2);
;         if (t <= lastvis) at_compute(lds, r32, hi, qr, t == 0, negm, m_run, l_run, o0, o1);
;         AT_ST(ka0, ka1, va, 1);
;         __syncthreads();
.Lpa_wEd_1:
	ds_write_b128 v173, v[104:107] offset:22528
	s_and_saveexec_b64 s[64:65], s[2:3]

; #define AT_LD(K0, K1, V, t) do { K0 = *(const u32x4*)(Kb + (size_t)(t) * 6144 + kp0 * 8); if (two) K1 = *(const u32x4*)(Kb + (size_t)(t) * 6144 + kp1 * 8); V = *(const u32x4*)(vsrc + (size_t)(t) * 64); } while (0)
; #define AT_ST(K0, K1, V, buf) do { LAS unsigned char* b_ = lds + (buf) * AT_TB; *(LAS u32x4*)(b_ + koff0) = K0; if (two) *(LAS u32x4*)(b_ + koff1) = K1; *(LAS u32x4*)(b_ + voffl) = V; } while (0)
; DEVI void attn_unit_p(int wv, LAS unsigned char* lds, const bf16_t* Qb, const float* ssq_q, const bf16_t* Kb, const bf16_t* VTb, int ldv, int NT, int vis0, bf16_t* Ob) {
;     ...
;         AT_ST(ka0, ka1, va, 1);
;         __syncthreads();
;         if (t + 3 < NT) AT_LD(ka0, ka1, va, t + 3);
.LBB0_1302:
	s_or_b64 exec, exec, s[64:65]
	s_add_i32 s64, s49, 3
	s_cmp_ge_u32 s64, s42
	s_nop 0
	ds_write_b128 v175, v[116:119] offset:35840
	s_waitcnt lgkmcnt(0)
	s_barrier
	s_cbranch_scc1 .LBB0_1316
	v_add_co_u32_e32 v2, vcc, 0x21919000, v14
	s_nop 1
	v_addc_co_u32_e32 v3, vcc, 0, v15, vcc
	global_load_dwordx4 v[104:107], v[2:3], off offset:2048
	s_and_saveexec_b64 s[64:65], s[2:3]
	s_cbranch_execz .LBB0_1305
	v_lshl_add_u64 v[2:3], s[54:55], 0, v[168:169]
	v_add_co_u32_e32 v2, vcc, 0x21919000, v2
	s_nop 1
	v_addc_co_u32_e32 v3, vcc, 0, v3, vcc
	global_load_dwordx4 v[108:111], v[2:3], off offset:2048

; DEVI unsigned cvtpk(float lo, float hi) { f32x2_t v = {lo, hi}; bf16x2_t b = __builtin_convertvector(v, bf16x2_t); return __builtin_bit_cast(unsigned, b); }
; #define MFMA32(a, b, c) __builtin_amdgcn_mfma_f32_32x32x16_bf16((a), (b), (c), 0, 0, 0)
; DEVI void at_compute(const LAS unsigned char* tb, int r32, int hi, const bf16x8 (&qr)[6], bool first, f32x16& negm, float& m_ref, float& l_run, f32x16& o0, f32x16& o1) {
;     ...
;     float rs = 0.f;
; #pragma unroll
;     for (int r = 0; r < 16; ++r) { p0[r] = __builtin_amdgcn_exp2f(p0[r]); p1[r] = __builtin_amdgcn_exp2f(p1[r]); rs += p0[r] + p1[r]; }
;     l_run += rs;
;     u32x4 pw[4];
; #pragma unroll
;     for (int s = 0; s < 2; ++s) {
;         pw[s] = (u32x4){cvtpk(p0[8 * s], p0[8 * s + 1]), cvtpk(p0[8 * s + 2], p0[8 * s + 3]), cvtpk(p0[8 * s + 4], p0[8 * s + 5]), cvtpk(p0[8 * s + 6], p0[8 * s + 7])};
;         pw[2 + s] = (u32x4){cvtpk(p1[8 * s], p1[8 * s + 1]), cvtpk(p1[8 * s + 2], p1[8 * s + 3]), cvtpk(p1[8 * s + 4], p1[8 * s + 5]), cvtpk(p1[8 * s + 6], p1[8 * s + 7])};
;     }
; #pragma unroll
;     for (int ks = 0; ks < 4; ++ks) {
;         const bf16x8 pb = __builtin_bit_cast(bf16x8, pw[ks]);
;         o0 = MFMA32(vf[2 * ks], pb, o0); o1 = MFMA32(vf[2 * ks + 1], pb, o1);
;     }
.LBB0_1315:
	v_exp_f32_e32 v179, v80
	v_exp_f32_e32 v182, v64
	v_exp_f32_e32 v0, v81
	v_exp_f32_e32 v80, v65
	v_exp_f32_e32 v183, v66
	v_add_f32_e32 v81, v182, v179
	v_exp_f32_e32 v184, v72
	v_pk_add_f32 v[64:65], v[80:81], v[0:1]
	v_exp_f32_e32 v81, v82
	v_pk_add_f32 v[180:181], v[64:65], v[64:65] op_sel_hi:[0,1]
	v_exp_f32_e32 v180, v83
	v_exp_f32_e32 v82, v67
	v_add_f32_e32 v83, v183, v81
	v_exp_f32_e32 v72, v73
	v_pk_add_f32 v[64:65], v[82:83], v[180:181]
	s_nop 0
	v_pk_add_f32 v[66:67], v[64:65], v[64:65] op_sel_hi:[0,1]
	v_exp_f32_e32 v83, v84
	v_exp_f32_e32 v181, v68
	v_exp_f32_e32 v66, v85
	v_exp_f32_e32 v68, v69
	v_add_f32_e32 v69, v181, v83
	v_pk_add_f32 v[64:65], v[68:69], v[66:67]
	s_nop 0
	v_pk_add_f32 v[84:85], v[64:65], v[64:65] op_sel_hi:[0,1]
	v_exp_f32_e32 v67, v86
	v_exp_f32_e32 v69, v70
	v_exp_f32_e32 v84, v87
	v_exp_f32_e32 v70, v71
	v_cvt_pk_bf16_f32 v66, v83, v66
	v_add_f32_e32 v71, v69, v67
	v_cvt_pk_bf16_f32 v67, v67, v84
	v_pk_add_f32 v[64:65], v[70:71], v[84:85]
	v_exp_f32_e32 v71, v88
	v_pk_add_f32 v[86:87], v[64:65], v[64:65] op_sel_hi:[0,1]
	v_exp_f32_e32 v86, v89
	v_add_f32_e32 v73, v184, v71
	v_pk_add_f32 v[64:65], v[72:73], v[86:87]
	s_nop 0
	v_pk_add_f32 v[88:89], v[64:65], v[64:65] op_sel_hi:[0,1]
	v_exp_f32_e32 v73, v90
	v_exp_f32_e32 v87, v74
	v_exp_f32_e32 v88, v91
	v_exp_f32_e32 v74, v75
	v_add_f32_e32 v75, v87, v73
	v_pk_add_f32 v[64:65], v[74:75], v[88:89]
	s_nop 0
	v_pk_add_f32 v[90:91], v[64:65], v[64:65] op_sel_hi:[0,1]
	v_exp_f32_e32 v75, v92
	v_cvt_pk_bf16_f32 v64, v179, v0
	v_exp_f32_e32 v0, v76
	v_exp_f32_e32 v90, v93
	v_exp_f32_e32 v76, v77
	v_cvt_pk_bf16_f32 v65, v81, v180
	v_add_f32_e32 v77, v0, v75
	v_pk_add_f32 v[84:85], v[76:77], v[90:91]
	v_mfma_f32_32x32x16_bf16 v[32:47], v[160:163], v[64:67], v[32:47]
	v_pk_add_f32 v[84:85], v[84:85], v[84:85] op_sel_hi:[0,1]
	v_exp_f32_e32 v77, v94
	v_exp_f32_e32 v84, v95
	v_mfma_f32_32x32x16_bf16 v[16:31], v[156:159], v[64:67], v[16:31]
	v_cvt_pk_bf16_f32 v64, v71, v86
	v_cvt_pk_bf16_f32 v65, v73, v88
	v_cvt_pk_bf16_f32 v66, v75, v90
	v_cvt_pk_bf16_f32 v67, v77, v84
	s_nop 1
	v_mfma_f32_32x32x16_bf16 v[32:47], v[148:151], v[64:67], v[32:47]
	v_mfma_f32_32x32x16_bf16 v[16:31], v[152:155], v[64:67], v[16:31]
	v_cvt_pk_bf16_f32 v64, v182, v80
	v_cvt_pk_bf16_f32 v65, v183, v82
	v_cvt_pk_bf16_f32 v66, v181, v68
	v_cvt_pk_bf16_f32 v67, v69, v70
	s_nop 1
	v_mfma_f32_32x32x16_bf16 v[32:47], v[10:13], v[64:67], v[32:47]
	v_cvt_pk_bf16_f32 v10, v184, v72
	v_cvt_pk_bf16_f32 v11, v87, v74
	v_cvt_pk_bf16_f32 v12, v0, v76
	v_mfma_f32_32x32x16_bf16 v[16:31], v[144:147], v[64:67], v[16:31]
	v_exp_f32_e32 v65, v78
	v_exp_f32_e32 v64, v79
	s_nop 0
	v_cvt_pk_bf16_f32 v13, v65, v64
	v_add_f32_e32 v65, v65, v77
	s_nop 0
	v_mfma_f32_32x32x16_bf16 v[32:47], v[6:9], v[10:13], v[32:47]
	v_add_f32_e64 v6, v64, v84
	v_add_f32_e64 v7, v65, v85
	v_add_f32_e32 v0, v6, v7
	v_add_f32_e32 v176, v176, v0
	v_mfma_f32_32x32x16_bf16 v[16:31], v[2:5], v[10:13], v[16:31]
	s_cmp_lg_u64 s[62:63], 0
	s_cbranch_scc0 .Lpa_wE0_0
	s_cmp_lg_u64 s[2:3], 0
	s_cbranch_scc0 .Lpa_wE2_0
	s_waitcnt vmcnt(3)
	s_branch .Lpa_wEd_0

; #define AT_LD(K0, K1, V, t) do { K0 = *(const u32x4*)(Kb + (size_t)(t) * 6144 + kp0 * 8); if (two) K1 = *(const u32x4*)(Kb + (size_t)(t) * 6144 + kp1 * 8); V = *(const u32x4*)(vsrc + (size_t)(t) * 64); } while (0)
; #define AT_ST(K0, K1, V, buf) do { LAS unsigned char* b_ = lds + (buf) * AT_TB; *(LAS u32x4*)(b_ + koff0) = K0; if (two) *(LAS u32x4*)(b_ + koff1) = K1; *(LAS u32x4*)(b_ + voffl) = V; } while (0)
; DEVI void attn_unit_p(int wv, LAS unsigned char* lds, const bf16_t* Qb, const float* ssq_q, const bf16_t* Kb, const bf16_t* VTb, int ldv, int NT, int vis0, bf16_t* Ob) {
;     ...
;     for (int t = 0; t < NT; t += 2) {
;         if (t + 2 < NT) AT_LD(kb0, kb1, vbb, t + 2);
;         if (t <= lastvis) at_compute(lds, r32, hi, qr, t == 0, negm, m_run, l_run, o0, o1);
;         AT_ST(ka0, ka1, va, 1);
;         __syncthreads();
.Lpa_wEd_0:
	ds_write_b128 v173, v[104:107] offset:22528
	s_and_saveexec_b64 s[64:65], s[2:3]
	s_cbranch_execnz .LBB0_1301
	s_branch .LBB0_1302

; #define AT_LD(K0, K1, V, t) do { K0 = *(const u32x4*)(Kb + (size_t)(t) * 6144 + kp0 * 8); if (two) K1 = *(const u32x4*)(Kb + (size_t)(t) * 6144 + kp1 * 8); V = *(const u32x4*)(vsrc + (size_t)(t) * 64); } while (0)
; #define AT_ST(K0, K1, V, buf) do { LAS unsigned char* b_ = lds + (buf) * AT_TB; *(LAS u32x4*)(b_ + koff0) = K0; if (two) *(LAS u32x4*)(b_ + koff1) = K1; *(LAS u32x4*)(b_ + voffl) = V; } while (0)
; DEVI void attn_unit_p(int wv, LAS unsigned char* lds, const bf16_t* Qb, const float* ssq_q, const bf16_t* Kb, const bf16_t* VTb, int ldv, int NT, int vis0, bf16_t* Ob) {
;     ...
;         if (t + 3 < NT) AT_LD(ka0, ka1, va, t + 3);
;         if (t + 1 <= lastvis) at_compute(lds + AT_TB, r32, hi, qr, false, negm, m_run, l_run, o0, o1);
;         if (t + 2 < NT) AT_ST(kb0, kb1, vbb, 0);
;         __syncthreads();
.LBB0_1320:
	s_add_i32 vcc_lo, s49, 3
	s_cmp_lt_u32 vcc_lo, s42
	s_cbranch_scc0 .Lpa_wO0
	s_cmp_lg_u64 s[2:3], 0
	s_cbranch_scc0 .Lpa_wO2
	s_waitcnt vmcnt(3)
	s_branch .Lpa_wOd

; #define AT_LD(K0, K1, V, t) do { K0 = *(const u32x4*)(Kb + (size_t)(t) * 6144 + kp0 * 8); if (two) K1 = *(const u32x4*)(Kb + (size_t)(t) * 6144 + kp1 * 8); V = *(const u32x4*)(vsrc + (size_t)(t) * 64); } while (0)
; #define AT_ST(K0, K1, V, buf) do { LAS unsigned char* b_ = lds + (buf) * AT_TB; *(LAS u32x4*)(b_ + koff0) = K0; if (two) *(LAS u32x4*)(b_ + koff1) = K1; *(LAS u32x4*)(b_ + voffl) = V; } while (0)
; DEVI void attn_unit_p(int wv, LAS unsigned char* lds, const bf16_t* Qb, const float* ssq_q, const bf16_t* Kb, const bf16_t* VTb, int ldv, int NT, int vis0, bf16_t* Ob) {
;     ...
;         if (t + 3 < NT) AT_LD(ka0, ka1, va, t + 3);
;         if (t + 1 <= lastvis) at_compute(lds + AT_TB, r32, hi, qr, false, negm, m_run, l_run, o0, o1);
;         if (t + 2 < NT) AT_ST(kb0, kb1, vbb, 0);
;         __syncthreads();
.Lpa_wO0:
	s_waitcnt vmcnt(0)
.Lpa_wOd:
	ds_write_b128 v173, v[96:99]
	s_and_saveexec_b64 s[62:63], s[2:3]
	ds_write_b128 v174, v[100:103]
	s_or_b64 exec, exec, s[62:63]
	ds_write_b128 v175, v[112:115] offset:13312

; DEVI void attn_phase(int wv, LAS unsigned char* lds, int l) {
;     ...
;         }
;     }
;     for (int bh = vcu; bh < 256; bh += G) sample_attn_fused(wv, lds, l, bh);
.LBB0_1326:
	s_setprio 0
	s_cmpk_gt_i32 s4, 0xff
	s_cbranch_scc1 .LBB0_1384
	v_readlane_b32 s2, v255, 7
	v_readlane_b32 s3, v255, 8
	s_mov_b32 s3, s13
	s_lshl_b64 s[6:7], s[46:47], 17
	s_lshl_b64 s[8:9], s[46:47], 9
	s_lshl_b64 s[10:11], s[12:13], 2
	s_lshl_b64 s[48:49], s[2:3], 2
	s_branch .LBB0_1330
